# grid barrier: XCD leaders poll the monotonic cross-XCD arrival counter instead of the generation word the last leader bumps afterwards (one fewer memory hop per barrier)
# baseline (speedup 1.0000x reference)
; __device__ __forceinline__ unsigned xb_ld(unsigned* p)              { return __hip_atomic_load(p, __ATOMIC_RELAXED, __HIP_MEMORY_SCOPE_AGENT); }
; __device__ __forceinline__ unsigned xb_add(unsigned* p, unsigned v) { return __hip_atomic_fetch_add(p, v, __ATOMIC_RELAXED, __HIP_MEMORY_SCOPE_AGENT); }
; #define XB_SPIN(cond, bar) do { unsigned _sp = 0; while (cond) { __builtin_amdgcn_s_sleep(1); \
;     if ((++_sp & 255u) == 0u) { if (xb_ld(&(bar)[XB_TMO])) break; if (_sp > XB_SPIN_CAP) { atomicAdd(&(bar)[XB_TMO], 1u); break; } } } } while (0)
; __device__ __forceinline__ void xcd_barrier(const XcdBarrier& b) {
;     ...
;         const unsigned old = xb_add(&bar[XB_XSUB(b.x)], 1u);
;         const unsigned gen = old / nloc;
;         if (old + 1u == (gen + 1u) * nloc) {
;             __builtin_amdgcn_fence(__ATOMIC_RELEASE, "agent");
;             asm volatile("s_waitcnt vmcnt(0)" ::: "memory");
;             const unsigned og = xb_add(&bar[XB_TOP], 1u);
;             const unsigned tg = og / nx;
;             if (og + 1u == (tg + 1u) * nx) xb_add(&bar[XB_TOPGEN], 1u);
;             else XB_SPIN(xb_ld(&bar[XB_TOPGEN]) == tg, bar);
.LBB0_66:
	s_or_b64 exec, exec, s[4:5]
	v_cvt_f32_u32_e32 v4, v1
	s_waitcnt vmcnt(0)
	v_readfirstlane_b32 s2, v3
	s_add_u32 s4, s70, 0x7500
	s_addc_u32 s5, s71, 0
	v_rcp_iflag_f32_e32 v4, v4
	v_add_u32_e32 v2, s2, v2
	v_add_u32_e32 v5, 1, v2
	s_mov_b64 s[6:7], -1
	v_mul_f32_e32 v3, 0x4f7ffffe, v4
	v_cvt_u32_f32_e32 v3, v3
	v_sub_u32_e32 v4, 0, v1
	v_mul_lo_u32 v4, v4, v3
	v_mul_hi_u32 v4, v3, v4
	v_add_u32_e32 v3, v3, v4
	v_mul_hi_u32 v3, v2, v3
	v_mul_lo_u32 v4, v3, v1
	v_sub_u32_e32 v2, v2, v4
	v_add_u32_e32 v6, 1, v3
	v_cmp_ge_u32_e32 vcc, v2, v1
	v_sub_u32_e32 v4, v2, v1
	s_nop 0
	v_cndmask_b32_e32 v3, v3, v6, vcc
	v_cndmask_b32_e32 v2, v2, v4, vcc
	v_add_u32_e32 v4, 1, v3
	v_cmp_ge_u32_e32 vcc, v2, v1
	s_nop 1
	v_cndmask_b32_e32 v4, v3, v4, vcc
	v_mul_lo_u32 v2, v1, v4
	v_add_u32_e32 v1, v2, v1
	v_cmp_ne_u32_e32 vcc, v5, v1
	v_mov_b32_e32 v28, v1
	v_mov_b64_e32 v[2:3], s[4:5]
	s_and_saveexec_b64 s[2:3], vcc
	s_cbranch_execz .LBB0_78
	v_mov_b32_e32 v1, 0
	global_load_dword v2, v1, s[4:5] offset:-256 sc1
	s_mov_b64 s[10:11], 0
	s_waitcnt vmcnt(0)
	v_cmp_lt_u32_e32 vcc, v2, v28
	s_and_saveexec_b64 s[8:9], vcc
	s_cbranch_execz .LBB0_77
	s_add_u32 s6, s70, 0x4200
	s_addc_u32 s7, s71, 0
	s_mov_b32 s22, 1
	s_branch .LBB0_70

; __device__ __forceinline__ unsigned xb_ld(unsigned* p)              { return __hip_atomic_load(p, __ATOMIC_RELAXED, __HIP_MEMORY_SCOPE_AGENT); }
; __device__ __forceinline__ unsigned xb_add(unsigned* p, unsigned v) { return __hip_atomic_fetch_add(p, v, __ATOMIC_RELAXED, __HIP_MEMORY_SCOPE_AGENT); }
; #define XB_SPIN(cond, bar) do { unsigned _sp = 0; while (cond) { __builtin_amdgcn_s_sleep(1); \
;     if ((++_sp & 255u) == 0u) { if (xb_ld(&(bar)[XB_TMO])) break; if (_sp > XB_SPIN_CAP) { atomicAdd(&(bar)[XB_TMO], 1u); break; } } } } while (0)
; __device__ __forceinline__ void xcd_barrier(const XcdBarrier& b) {
;     ...
;             const unsigned og = xb_add(&bar[XB_TOP], 1u);
;             const unsigned tg = og / nx;
;             if (og + 1u == (tg + 1u) * nx) xb_add(&bar[XB_TOPGEN], 1u);
;             else XB_SPIN(xb_ld(&bar[XB_TOPGEN]) == tg, bar);
.LBB0_72:
	global_load_dword v2, v1, s[4:5] offset:-256 sc1
	s_add_i32 s22, s22, 1
	s_mov_b64 s[14:15], -1
	s_waitcnt vmcnt(0)
	v_cmp_ge_u32_e32 vcc, v2, v28
	s_orn2_b64 s[18:19], vcc, exec
	s_branch .LBB0_69

; __device__ __forceinline__ unsigned xb_ld(unsigned* p)              { return __hip_atomic_load(p, __ATOMIC_RELAXED, __HIP_MEMORY_SCOPE_AGENT); }
; __device__ __forceinline__ unsigned xb_add(unsigned* p, unsigned v) { return __hip_atomic_fetch_add(p, v, __ATOMIC_RELAXED, __HIP_MEMORY_SCOPE_AGENT); }
; #define XB_SPIN(cond, bar) do { unsigned _sp = 0; while (cond) { __builtin_amdgcn_s_sleep(1); \
;     if ((++_sp & 255u) == 0u) { if (xb_ld(&(bar)[XB_TMO])) break; if (_sp > XB_SPIN_CAP) { atomicAdd(&(bar)[XB_TMO], 1u); break; } } } } while (0)
; __device__ __forceinline__ void xcd_barrier(const XcdBarrier& b) {
;     ...
;         const unsigned old = xb_add(&bar[XB_XSUB(b.x)], 1u);
;         const unsigned gen = old / nloc;
;         if (old + 1u == (gen + 1u) * nloc) {
;             __builtin_amdgcn_fence(__ATOMIC_RELEASE, "agent");
;             asm volatile("s_waitcnt vmcnt(0)" ::: "memory");
;             const unsigned og = xb_add(&bar[XB_TOP], 1u);
;             const unsigned tg = og / nx;
;             if (og + 1u == (tg + 1u) * nx) xb_add(&bar[XB_TOPGEN], 1u);
;             else XB_SPIN(xb_ld(&bar[XB_TOPGEN]) == tg, bar);
.LBB0_371:
	s_or_b64 exec, exec, s[8:9]
	v_cvt_f32_u32_e32 v4, v2
	s_waitcnt vmcnt(0)
	v_readfirstlane_b32 s6, v3
	s_mov_b64 s[8:9], -1
	v_rcp_iflag_f32_e32 v4, v4
	v_add_u32_e32 v1, s6, v1
	v_add_u32_e32 v5, 1, v1
	v_readlane_b32 s6, v253, 39
	v_mul_f32_e32 v3, 0x4f7ffffe, v4
	v_cvt_u32_f32_e32 v3, v3
	v_sub_u32_e32 v4, 0, v2
	v_readlane_b32 s7, v253, 40
	v_mul_lo_u32 v4, v4, v3
	v_mul_hi_u32 v4, v3, v4
	v_add_u32_e32 v3, v3, v4
	v_mul_hi_u32 v3, v1, v3
	v_mul_lo_u32 v4, v3, v2
	v_sub_u32_e32 v1, v1, v4
	v_add_u32_e32 v6, 1, v3
	v_cmp_ge_u32_e32 vcc, v1, v2
	v_sub_u32_e32 v4, v1, v2
	s_nop 0
	v_cndmask_b32_e32 v3, v3, v6, vcc
	v_cndmask_b32_e32 v1, v1, v4, vcc
	v_add_u32_e32 v4, 1, v3
	v_cmp_ge_u32_e32 vcc, v1, v2
	s_nop 1
	v_cndmask_b32_e32 v1, v3, v4, vcc
	v_mul_lo_u32 v3, v2, v1
	v_add_u32_e32 v2, v3, v2
	v_cmp_ne_u32_e32 vcc, v5, v2
	v_mov_b32_e32 v28, v2
	v_mov_b64_e32 v[2:3], s[6:7]
	s_and_saveexec_b64 s[6:7], vcc
	s_cbranch_execz .LBB0_383
	v_readlane_b32 s8, v253, 39
	v_readlane_b32 s9, v253, 40
	s_mov_b64 s[16:17], 0
	s_nop 3
	global_load_dword v2, v33, s[8:9] offset:-256 sc1
	s_waitcnt vmcnt(0)
	v_cmp_lt_u32_e32 vcc, v2, v28
	s_and_saveexec_b64 s[8:9], vcc
	s_cbranch_execz .LBB0_382
	s_mov_b32 s30, 1
	s_branch .LBB0_375

; __device__ __forceinline__ unsigned xb_ld(unsigned* p)              { return __hip_atomic_load(p, __ATOMIC_RELAXED, __HIP_MEMORY_SCOPE_AGENT); }
; __device__ __forceinline__ unsigned xb_add(unsigned* p, unsigned v) { return __hip_atomic_fetch_add(p, v, __ATOMIC_RELAXED, __HIP_MEMORY_SCOPE_AGENT); }
; #define XB_SPIN(cond, bar) do { unsigned _sp = 0; while (cond) { __builtin_amdgcn_s_sleep(1); \
;     if ((++_sp & 255u) == 0u) { if (xb_ld(&(bar)[XB_TMO])) break; if (_sp > XB_SPIN_CAP) { atomicAdd(&(bar)[XB_TMO], 1u); break; } } } } while (0)
; __device__ __forceinline__ void xcd_barrier(const XcdBarrier& b) {
;     ...
;             const unsigned og = xb_add(&bar[XB_TOP], 1u);
;             const unsigned tg = og / nx;
;             if (og + 1u == (tg + 1u) * nx) xb_add(&bar[XB_TOPGEN], 1u);
;             else XB_SPIN(xb_ld(&bar[XB_TOPGEN]) == tg, bar);
.LBB0_377:
	v_readlane_b32 s10, v253, 39
	v_readlane_b32 s11, v253, 40
	s_add_i32 s30, s30, 1
	s_mov_b64 s[26:27], -1
	s_nop 2
	global_load_dword v2, v33, s[10:11] offset:-256 sc1
	s_waitcnt vmcnt(0)
	v_cmp_ge_u32_e32 vcc, v2, v28
	s_orn2_b64 s[24:25], vcc, exec
	s_branch .LBB0_374

; __device__ __forceinline__ unsigned xb_ld(unsigned* p)              { return __hip_atomic_load(p, __ATOMIC_RELAXED, __HIP_MEMORY_SCOPE_AGENT); }
; __device__ __forceinline__ unsigned xb_add(unsigned* p, unsigned v) { return __hip_atomic_fetch_add(p, v, __ATOMIC_RELAXED, __HIP_MEMORY_SCOPE_AGENT); }
; #define XB_SPIN(cond, bar) do { unsigned _sp = 0; while (cond) { __builtin_amdgcn_s_sleep(1); \
;     if ((++_sp & 255u) == 0u) { if (xb_ld(&(bar)[XB_TMO])) break; if (_sp > XB_SPIN_CAP) { atomicAdd(&(bar)[XB_TMO], 1u); break; } } } } while (0)
; __device__ __forceinline__ void xcd_barrier(const XcdBarrier& b) {
;     ...
;         const unsigned old = xb_add(&bar[XB_XSUB(b.x)], 1u);
;         const unsigned gen = old / nloc;
;         if (old + 1u == (gen + 1u) * nloc) {
;             __builtin_amdgcn_fence(__ATOMIC_RELEASE, "agent");
;             asm volatile("s_waitcnt vmcnt(0)" ::: "memory");
;             const unsigned og = xb_add(&bar[XB_TOP], 1u);
;             const unsigned tg = og / nx;
;             if (og + 1u == (tg + 1u) * nx) xb_add(&bar[XB_TOPGEN], 1u);
;             else XB_SPIN(xb_ld(&bar[XB_TOPGEN]) == tg, bar);
.LBB0_517:
	s_or_b64 exec, exec, s[6:7]
	s_waitcnt vmcnt(0)
	v_readfirstlane_b32 s4, v3
	v_sub_u32_e32 v4, 0, v2
	s_mov_b64 s[6:7], -1
	v_add_u32_e32 v3, s4, v1
	v_cvt_f32_u32_e32 v1, v2
	v_readlane_b32 s4, v253, 39
	v_readlane_b32 s5, v253, 40
	v_rcp_iflag_f32_e32 v1, v1
	s_nop 0
	v_mul_f32_e32 v1, 0x4f7ffffe, v1
	v_cvt_u32_f32_e32 v1, v1
	v_mul_lo_u32 v4, v4, v1
	v_mul_hi_u32 v4, v1, v4
	v_add_u32_e32 v1, v1, v4
	v_mul_hi_u32 v1, v3, v1
	v_mul_lo_u32 v4, v1, v2
	v_sub_u32_e32 v4, v3, v4
	v_cmp_ge_u32_e32 vcc, v4, v2
	v_add_u32_e32 v5, 1, v1
	v_add_u32_e32 v3, 1, v3
	v_cndmask_b32_e32 v1, v1, v5, vcc
	v_sub_u32_e32 v5, v4, v2
	v_cndmask_b32_e32 v4, v4, v5, vcc
	v_cmp_ge_u32_e32 vcc, v4, v2
	v_add_u32_e32 v4, 1, v1
	s_nop 0
	v_cndmask_b32_e32 v1, v1, v4, vcc
	v_mul_lo_u32 v4, v2, v1
	v_add_u32_e32 v2, v4, v2
	v_cmp_ne_u32_e32 vcc, v3, v2
	v_mov_b32_e32 v28, v2
	v_mov_b64_e32 v[2:3], s[4:5]
	s_and_saveexec_b64 s[4:5], vcc
	s_cbranch_execz .LBB0_529
	v_readlane_b32 s6, v253, 39
	v_readlane_b32 s7, v253, 40
	s_mov_b64 s[8:9], 0
	s_nop 3
	global_load_dword v2, v33, s[6:7] offset:-256 sc1
	s_waitcnt vmcnt(0)
	v_cmp_lt_u32_e32 vcc, v2, v28
	s_and_saveexec_b64 s[6:7], vcc
	s_cbranch_execz .LBB0_528
	s_mov_b32 s18, 1
	s_branch .LBB0_521

; __device__ __forceinline__ unsigned xb_ld(unsigned* p)              { return __hip_atomic_load(p, __ATOMIC_RELAXED, __HIP_MEMORY_SCOPE_AGENT); }
; __device__ __forceinline__ unsigned xb_add(unsigned* p, unsigned v) { return __hip_atomic_fetch_add(p, v, __ATOMIC_RELAXED, __HIP_MEMORY_SCOPE_AGENT); }
; #define XB_SPIN(cond, bar) do { unsigned _sp = 0; while (cond) { __builtin_amdgcn_s_sleep(1); \
;     if ((++_sp & 255u) == 0u) { if (xb_ld(&(bar)[XB_TMO])) break; if (_sp > XB_SPIN_CAP) { atomicAdd(&(bar)[XB_TMO], 1u); break; } } } } while (0)
; __device__ __forceinline__ void xcd_barrier(const XcdBarrier& b) {
;     ...
;             const unsigned og = xb_add(&bar[XB_TOP], 1u);
;             const unsigned tg = og / nx;
;             if (og + 1u == (tg + 1u) * nx) xb_add(&bar[XB_TOPGEN], 1u);
;             else XB_SPIN(xb_ld(&bar[XB_TOPGEN]) == tg, bar);
.LBB0_523:
	v_readlane_b32 s12, v253, 39
	v_readlane_b32 s13, v253, 40
	s_add_i32 s18, s18, 1
	s_mov_b64 s[14:15], -1
	s_nop 2
	global_load_dword v2, v33, s[12:13] offset:-256 sc1
	s_waitcnt vmcnt(0)
	v_cmp_ge_u32_e32 vcc, v2, v28
	s_orn2_b64 s[12:13], vcc, exec
	s_branch .LBB0_520

; __device__ __forceinline__ unsigned xb_ld(unsigned* p)              { return __hip_atomic_load(p, __ATOMIC_RELAXED, __HIP_MEMORY_SCOPE_AGENT); }
; __device__ __forceinline__ unsigned xb_add(unsigned* p, unsigned v) { return __hip_atomic_fetch_add(p, v, __ATOMIC_RELAXED, __HIP_MEMORY_SCOPE_AGENT); }
; #define XB_SPIN(cond, bar) do { unsigned _sp = 0; while (cond) { __builtin_amdgcn_s_sleep(1); \
;     if ((++_sp & 255u) == 0u) { if (xb_ld(&(bar)[XB_TMO])) break; if (_sp > XB_SPIN_CAP) { atomicAdd(&(bar)[XB_TMO], 1u); break; } } } } while (0)
; __device__ __forceinline__ void xcd_barrier(const XcdBarrier& b) {
;     ...
;         const unsigned old = xb_add(&bar[XB_XSUB(b.x)], 1u);
;         const unsigned gen = old / nloc;
;         if (old + 1u == (gen + 1u) * nloc) {
;             __builtin_amdgcn_fence(__ATOMIC_RELEASE, "agent");
;             asm volatile("s_waitcnt vmcnt(0)" ::: "memory");
;             const unsigned og = xb_add(&bar[XB_TOP], 1u);
;             const unsigned tg = og / nx;
;             if (og + 1u == (tg + 1u) * nx) xb_add(&bar[XB_TOPGEN], 1u);
;             else XB_SPIN(xb_ld(&bar[XB_TOPGEN]) == tg, bar);
.LBB0_1227:
	s_or_b64 exec, exec, s[8:9]
	s_waitcnt vmcnt(0)
	v_readfirstlane_b32 s3, v3
	v_sub_u32_e32 v4, 0, v2
	v_readlane_b32 s6, v253, 39
	v_add_u32_e32 v3, s3, v1
	v_cvt_f32_u32_e32 v1, v2
	v_readlane_b32 s7, v253, 40
	s_mov_b64 s[8:9], -1
	v_rcp_iflag_f32_e32 v1, v1
	s_nop 0
	v_mul_f32_e32 v1, 0x4f7ffffe, v1
	v_cvt_u32_f32_e32 v1, v1
	v_mul_lo_u32 v4, v4, v1
	v_mul_hi_u32 v4, v1, v4
	v_add_u32_e32 v1, v1, v4
	v_mul_hi_u32 v1, v3, v1
	v_mul_lo_u32 v4, v1, v2
	v_sub_u32_e32 v4, v3, v4
	v_cmp_ge_u32_e32 vcc, v4, v2
	v_add_u32_e32 v5, 1, v1
	v_add_u32_e32 v3, 1, v3
	v_cndmask_b32_e32 v1, v1, v5, vcc
	v_sub_u32_e32 v5, v4, v2
	v_cndmask_b32_e32 v4, v4, v5, vcc
	v_cmp_ge_u32_e32 vcc, v4, v2
	v_add_u32_e32 v4, 1, v1
	s_nop 0
	v_cndmask_b32_e32 v1, v1, v4, vcc
	v_mul_lo_u32 v4, v2, v1
	v_add_u32_e32 v2, v4, v2
	v_cmp_ne_u32_e32 vcc, v3, v2
	v_mov_b32_e32 v28, v2
	v_mov_b64_e32 v[2:3], s[6:7]
	s_and_saveexec_b64 s[6:7], vcc
	s_cbranch_execz .LBB0_1239
	v_readlane_b32 s8, v253, 39
	v_readlane_b32 s9, v253, 40
	s_mov_b64 s[12:13], 0
	s_nop 3
	global_load_dword v2, v33, s[8:9] offset:-256 sc1
	s_waitcnt vmcnt(0)
	v_cmp_lt_u32_e32 vcc, v2, v28
	s_and_saveexec_b64 s[8:9], vcc
	s_cbranch_execz .LBB0_1238
	s_mov_b32 s3, 1
	s_branch .LBB0_1231

; __device__ __forceinline__ unsigned xb_ld(unsigned* p)              { return __hip_atomic_load(p, __ATOMIC_RELAXED, __HIP_MEMORY_SCOPE_AGENT); }
; __device__ __forceinline__ unsigned xb_add(unsigned* p, unsigned v) { return __hip_atomic_fetch_add(p, v, __ATOMIC_RELAXED, __HIP_MEMORY_SCOPE_AGENT); }
; #define XB_SPIN(cond, bar) do { unsigned _sp = 0; while (cond) { __builtin_amdgcn_s_sleep(1); \
;     if ((++_sp & 255u) == 0u) { if (xb_ld(&(bar)[XB_TMO])) break; if (_sp > XB_SPIN_CAP) { atomicAdd(&(bar)[XB_TMO], 1u); break; } } } } while (0)
; __device__ __forceinline__ void xcd_barrier(const XcdBarrier& b) {
;     ...
;             const unsigned og = xb_add(&bar[XB_TOP], 1u);
;             const unsigned tg = og / nx;
;             if (og + 1u == (tg + 1u) * nx) xb_add(&bar[XB_TOPGEN], 1u);
;             else XB_SPIN(xb_ld(&bar[XB_TOPGEN]) == tg, bar);
.LBB0_1233:
	v_readlane_b32 s16, v253, 39
	v_readlane_b32 s17, v253, 40
	s_add_i32 s3, s3, 1
	s_mov_b64 s[18:19], -1
	s_nop 2
	global_load_dword v2, v33, s[16:17] offset:-256 sc1
	s_waitcnt vmcnt(0)
	v_cmp_ge_u32_e32 vcc, v2, v28
	s_orn2_b64 s[16:17], vcc, exec
	s_branch .LBB0_1230

; __device__ __forceinline__ unsigned xb_ld(unsigned* p)              { return __hip_atomic_load(p, __ATOMIC_RELAXED, __HIP_MEMORY_SCOPE_AGENT); }
; __device__ __forceinline__ unsigned xb_add(unsigned* p, unsigned v) { return __hip_atomic_fetch_add(p, v, __ATOMIC_RELAXED, __HIP_MEMORY_SCOPE_AGENT); }
; #define XB_SPIN(cond, bar) do { unsigned _sp = 0; while (cond) { __builtin_amdgcn_s_sleep(1); \
;     if ((++_sp & 255u) == 0u) { if (xb_ld(&(bar)[XB_TMO])) break; if (_sp > XB_SPIN_CAP) { atomicAdd(&(bar)[XB_TMO], 1u); break; } } } } while (0)
; __device__ __forceinline__ void xcd_barrier(const XcdBarrier& b) {
;     ...
;         const unsigned old = xb_add(&bar[XB_XSUB(b.x)], 1u);
;         const unsigned gen = old / nloc;
;         if (old + 1u == (gen + 1u) * nloc) {
;             __builtin_amdgcn_fence(__ATOMIC_RELEASE, "agent");
;             asm volatile("s_waitcnt vmcnt(0)" ::: "memory");
;             const unsigned og = xb_add(&bar[XB_TOP], 1u);
;             const unsigned tg = og / nx;
;             if (og + 1u == (tg + 1u) * nx) xb_add(&bar[XB_TOPGEN], 1u);
;             else XB_SPIN(xb_ld(&bar[XB_TOPGEN]) == tg, bar);
.LBB0_1288:
	s_or_b64 exec, exec, s[8:9]
	s_waitcnt vmcnt(0)
	v_readfirstlane_b32 s3, v3
	v_sub_u32_e32 v4, 0, v2
	v_readlane_b32 s6, v253, 39
	v_add_u32_e32 v3, s3, v1
	v_cvt_f32_u32_e32 v1, v2
	v_readlane_b32 s7, v253, 40
	s_mov_b64 s[8:9], -1
	v_rcp_iflag_f32_e32 v1, v1
	s_nop 0
	v_mul_f32_e32 v1, 0x4f7ffffe, v1
	v_cvt_u32_f32_e32 v1, v1
	v_mul_lo_u32 v4, v4, v1
	v_mul_hi_u32 v4, v1, v4
	v_add_u32_e32 v1, v1, v4
	v_mul_hi_u32 v1, v3, v1
	v_mul_lo_u32 v4, v1, v2
	v_sub_u32_e32 v4, v3, v4
	v_cmp_ge_u32_e32 vcc, v4, v2
	v_add_u32_e32 v5, 1, v1
	v_add_u32_e32 v3, 1, v3
	v_cndmask_b32_e32 v1, v1, v5, vcc
	v_sub_u32_e32 v5, v4, v2
	v_cndmask_b32_e32 v4, v4, v5, vcc
	v_cmp_ge_u32_e32 vcc, v4, v2
	v_add_u32_e32 v4, 1, v1
	s_nop 0
	v_cndmask_b32_e32 v1, v1, v4, vcc
	v_mul_lo_u32 v4, v2, v1
	v_add_u32_e32 v2, v4, v2
	v_cmp_ne_u32_e32 vcc, v3, v2
	v_mov_b32_e32 v28, v2
	v_mov_b64_e32 v[2:3], s[6:7]
	s_and_saveexec_b64 s[6:7], vcc
	s_cbranch_execz .LBB0_1300
	v_readlane_b32 s8, v253, 39
	v_readlane_b32 s9, v253, 40
	s_mov_b64 s[10:11], 0
	s_nop 3
	global_load_dword v2, v33, s[8:9] offset:-256 sc1
	s_waitcnt vmcnt(0)
	v_cmp_lt_u32_e32 vcc, v2, v28
	s_and_saveexec_b64 s[8:9], vcc
	s_cbranch_execz .LBB0_1299
	s_mov_b32 s3, 1
	s_branch .LBB0_1292

; __device__ __forceinline__ unsigned xb_ld(unsigned* p)              { return __hip_atomic_load(p, __ATOMIC_RELAXED, __HIP_MEMORY_SCOPE_AGENT); }
; __device__ __forceinline__ unsigned xb_add(unsigned* p, unsigned v) { return __hip_atomic_fetch_add(p, v, __ATOMIC_RELAXED, __HIP_MEMORY_SCOPE_AGENT); }
; #define XB_SPIN(cond, bar) do { unsigned _sp = 0; while (cond) { __builtin_amdgcn_s_sleep(1); \
;     if ((++_sp & 255u) == 0u) { if (xb_ld(&(bar)[XB_TMO])) break; if (_sp > XB_SPIN_CAP) { atomicAdd(&(bar)[XB_TMO], 1u); break; } } } } while (0)
; __device__ __forceinline__ void xcd_barrier(const XcdBarrier& b) {
;     ...
;             const unsigned og = xb_add(&bar[XB_TOP], 1u);
;             const unsigned tg = og / nx;
;             if (og + 1u == (tg + 1u) * nx) xb_add(&bar[XB_TOPGEN], 1u);
;             else XB_SPIN(xb_ld(&bar[XB_TOPGEN]) == tg, bar);
.LBB0_1294:
	v_readlane_b32 s14, v253, 39
	v_readlane_b32 s15, v253, 40
	s_add_i32 s3, s3, 1
	s_mov_b64 s[16:17], -1
	s_nop 2
	global_load_dword v2, v33, s[14:15] offset:-256 sc1
	s_waitcnt vmcnt(0)
	v_cmp_ge_u32_e32 vcc, v2, v28
	s_orn2_b64 s[14:15], vcc, exec
	s_branch .LBB0_1291
